# P3 start: j0-table copy loads issued with the gamma loads ahead of the abs-max butterfly instead of a serial load-wait-write loop after it, on p0h
# speedup vs baseline: 1.0001x; 1.0001x over previous
; template<int THRL,class Extra> __device__ __forceinline__ void attn_phase_dyn(char*lds,const AttnTensors&T,unsigned*ctr,const Extra&X,int nextra){
;   const int tid=threadIdx.x;
;   volatile __attribute__((address_space(3))) unsigned* uw=(volatile __attribute__((address_space(3))) unsigned*)((__attribute__((address_space(3))) char*)lds+LDS_WS);
;   volatile __attribute__((address_space(3))) int* jt=(volatile __attribute__((address_space(3))) int*)((__attribute__((address_space(3))) char*)lds+LDS_J0);
;   for(int i=tid;i<BATCH*NHEAD*NQB;i+=NW*64)jt[i]=((const int*)(T.ws+T.oj0))[i];
;   const unsigned G_=gridDim.x; unsigned nxt=blockIdx.x;
; __device__ __forceinline__ float qk_bound(const float* q_g, const float* k_g, int lane) {
;     float gq = fabsf(q_g[lane]), gk = fabsf(k_g[lane]);
; #pragma unroll
;     for (int o = 1; o < 64; o <<= 1) { gq = fmaxf(gq, __shfl_xor(gq, o)); gk = fmaxf(gk, __shfl_xor(gk, o)); }
;     return attn_body::C2 * 64.0f * 1.02f * gq * gk;
; }
.LBB0_337:
	s_or_b64 exec, exec, s[4:5]
	s_mov_b64 s[4:5], s[0:1]
	s_waitcnt lgkmcnt(0)
	s_barrier
	v_mov_b32_e32 v2, v0
	s_mov_b32 s3, s2
	s_load_dwordx4 s[8:11], s[4:5], 0x38
	s_load_dwordx2 s[6:7], s[4:5], 0x70
	s_load_dword s3, s[24:25], 0x0
	v_and_b32_e32 v2, 63, v2
	v_lshlrev_b32_e32 v2, 2, v2
	v_or_b32_e32 v8, 0xfffffe00, v0
	s_waitcnt lgkmcnt(0)
	s_add_u32 s86, s6, 0x1c000000
	s_addc_u32 s87, s7, 0
	s_mov_b32 s4, s3
	global_load_dword v3, v2, s[8:9]
	global_load_dword v4, v2, s[10:11]
	s_mov_b64 s[4:5], 0x1c100000
	s_mov_b64 s[8:9], 0x800
	v_lshlrev_b32_e32 v20, 2, v0
	v_mov_b32_e32 v21, 0
	v_lshl_add_u64 v[20:21], s[6:7], 0, v[20:21]
	v_lshl_add_u64 v[20:21], v[20:21], 0, s[4:5]
	global_load_dword v22, v[20:21], off
	global_load_dword v23, v[20:21], off offset:2048
	s_waitcnt vmcnt(3)
	v_and_b32_e32 v2, 0x7fffffff, v3
	s_waitcnt vmcnt(2)
	v_and_b32_e32 v5, 0x7fffffff, v4
	ds_bpermute_b32 v2, v165, v2
	ds_bpermute_b32 v5, v165, v5
	v_max_f32_e64 v3, |v3|, |v3|
	v_max_f32_e64 v4, |v4|, |v4|
	s_waitcnt lgkmcnt(1)
	v_max_f32_e32 v2, v2, v2
	s_waitcnt lgkmcnt(0)
	v_max_f32_e32 v5, v5, v5
	v_max_f32_e32 v2, v3, v2
	v_max_f32_e32 v3, v4, v5
	ds_bpermute_b32 v4, v169, v2
	ds_bpermute_b32 v5, v169, v3
	s_waitcnt lgkmcnt(1)
	v_max_f32_e32 v4, v4, v4
	s_waitcnt lgkmcnt(0)
	v_max_f32_e32 v5, v5, v5
	v_max_f32_e32 v2, v2, v4
	v_max_f32_e32 v3, v3, v5
	ds_bpermute_b32 v4, v168, v2
	ds_bpermute_b32 v5, v168, v3
	s_waitcnt lgkmcnt(1)
	v_max_f32_e32 v4, v4, v4
	s_waitcnt lgkmcnt(0)
	v_max_f32_e32 v5, v5, v5
	v_max_f32_e32 v4, v2, v4
	v_max_f32_e32 v5, v3, v5
	ds_bpermute_b32 v6, v167, v4
	ds_bpermute_b32 v7, v167, v5
	v_lshlrev_b32_e32 v2, 2, v0
	v_mov_b32_e32 v3, 0
	v_add_u32_e32 v9, 0, v2
	s_waitcnt lgkmcnt(1)
	v_max_f32_e32 v6, v6, v6
	s_waitcnt lgkmcnt(0)
	v_max_f32_e32 v7, v7, v7
	v_max_f32_e32 v4, v4, v6
	v_max_f32_e32 v6, v5, v7
	ds_bpermute_b32 v5, v166, v4
	ds_bpermute_b32 v7, v166, v6
	v_lshl_add_u64 v[2:3], s[6:7], 0, v[2:3]
	v_add_u32_e32 v9, 0x18800, v9
	v_lshl_add_u64 v[2:3], v[2:3], 0, s[4:5]
	s_waitcnt lgkmcnt(1)
	v_max_f32_e32 v5, v5, v5
	s_waitcnt lgkmcnt(0)
	v_max_f32_e32 v7, v7, v7
	v_max_f32_e32 v5, v4, v5
	v_max_f32_e32 v4, v6, v7
	ds_bpermute_b32 v7, v164, v5
	ds_bpermute_b32 v6, v164, v4
	s_waitcnt vmcnt(0)
	ds_write_b32 v9, v22
	ds_write_b32 v9, v23 offset:2048
	s_cmp_lg_u32 0, -1
	s_cselect_b32 s4, 0, 0
	s_addk_i32 s4, 0x6000
	s_add_i32 s8, 0, 0x14800
	s_add_u32 s14, s6, 0x43800
	s_addc_u32 s15, s7, 0
	s_add_u32 s47, s6, 0x6000000
	s_addc_u32 s48, s7, 0
	s_add_u32 s49, s6, 0x8000000
	s_addc_u32 s50, s7, 0
	s_waitcnt lgkmcnt(2)
	v_max_f32_e32 v7, v7, v7
	v_max_f32_e32 v5, v5, v5
	s_add_u32 s51, s6, 0xa000000
	v_lshlrev_b32_e32 v3, 1, v0
	v_and_b32_e32 v205, 31, v0
	v_bfe_u32 v198, v0, 5, 1
	v_lshlrev_b32_e32 v10, 4, v0
	v_max_f32_e32 v5, v5, v7
	s_waitcnt lgkmcnt(1)
	v_max_f32_e32 v6, v6, v6
	v_max_f32_e32 v4, v4, v4
	s_addc_u32 s52, s7, 0
	v_mov_b32_e32 v201, 0
	v_and_b32_e32 v3, 32, v3
	v_and_b32_e32 v11, 0xc0, v10
	v_lshlrev_b32_e32 v12, 10, v198
	v_lshlrev_b32_e32 v13, 4, v205
	v_bfe_u32 v233, v0, 3, 3
	v_max_f32_e32 v4, v4, v6
	v_mul_f32_e32 v5, 0x413c5bb7, v5
	s_add_u32 s53, s6, 0xc000000
	v_and_b32_e32 v8, 24, v170
	v_add_u32_e32 v9, s4, v3
	v_add_u32_e32 v3, 0, v3
	v_lshlrev_b32_e32 v10, 9, v205
	v_add3_u32 v207, 0, v12, v13
	v_lshlrev_b32_e32 v13, 4, v198
	v_lshlrev_b32_e32 v202, 5, v0
	v_lshlrev_b32_e32 v15, 6, v0
	v_or_b32_e32 v17, 8, v233
	v_or_b32_e32 v19, 16, v233
	v_or_b32_e32 v20, 24, v233
	v_mul_f32_e32 v237, v5, v4
	v_lshl_or_b32 v4, v198, 8, v11
	v_mov_b32_e32 v203, v201
	s_addc_u32 s54, s7, 0
	v_lshlrev_b32_e32 v2, 9, v1
	v_lshl_or_b32 v10, v198, 3, v10
	v_lshlrev_b32_e32 v232, 2, v198
	v_lshlrev_b32_e32 v12, 10, v233
	v_lshlrev_b32_e32 v14, 10, v17
	v_lshlrev_b32_e32 v16, 10, v19
	v_lshlrev_b32_e32 v18, 10, v20
	v_add3_u32 v238, v9, v8, v4
	v_add3_u32 v239, v3, v8, v4
	v_add_u32_e32 v240, s8, v13
	v_and_b32_e32 v4, 0xe00, v15
	v_lshl_add_u64 v[6:7], s[6:7], 0, v[202:203]
	s_mov_b64 s[8:9], 0x1c000000
	s_add_u32 s55, s6, 0x2000000
	v_add_u32_e32 v3, 0, v13
	s_mov_b32 s28, 0xffff0000
	s_mov_b32 s13, 0
	s_movk_i32 s33, 0x6000
	v_and_b32_e32 v204, 56, v170
	v_cmp_gt_u32_e64 s[4:5], 32, v1
	v_lshlrev_b32_e32 v206, 3, v1
	v_or_b32_e32 v241, 0xc0, v232
	v_or_b32_e32 v253, 0xf3, v232
	v_or_b32_e32 v236, 0xf8, v232
	v_or_b32_e32 v244, 0xf9, v232
	v_or_b32_e32 v245, 0xfa, v232
	v_or_b32_e32 v246, 0xfb, v232
	v_lshlrev_b32_e32 v247, 9, v198
	v_lshlrev_b32_e32 v248, 7, v233
	v_lshlrev_b32_e32 v249, 7, v17
	v_lshlrev_b32_e32 v250, 7, v19
	v_lshlrev_b32_e32 v251, 7, v20
	s_movk_i32 s46, 0x84
	v_lshl_add_u64 v[208:209], v[6:7], 0, s[8:9]
	s_addc_u32 s56, s7, 0
	v_mov_b32_e32 v199, v198
	v_add_u32_e32 v203, 0x14a00, v3
	v_add_u32_e32 v254, 0x14900, v3
	v_lshlrev_b32_e32 v210, 4, v1
	v_mov_b32_e32 v211, v201
	v_mov_b32_e32 v213, s2
	v_lshlrev_b32_e32 v234, 1, v2
	v_lshlrev_b32_e32 v214, 1, v8
	s_mov_b64 s[16:17], 0x10000
	s_movk_i32 s57, 0x2000
	v_lshlrev_b32_e32 v255, 1, v10
	s_mov_b64 s[20:21], 0x20000
	s_movk_i32 s58, 0x4000
	s_mov_b64 s[22:23], 0x30000
	s_mov_b64 s[26:27], 0x50000
	s_mov_b32 s29, -1
	v_lshlrev_b32_e32 v216, 1, v4
	v_lshlrev_b32_e32 v218, 1, v12
	v_lshlrev_b32_e32 v220, 1, v14
	v_lshlrev_b32_e32 v222, 1, v16
	v_lshlrev_b32_e32 v224, 1, v18
	s_mov_b64 s[30:31], 0x1000
	s_mov_b32 s59, 0xe000000
	s_brev_b32 s60, 8
	s_brev_b32 s61, 64
	s_mov_b32 s62, 0x2001000
	s_mov_b64 s[34:35], 0x1000000
	s_mov_b64 s[36:37], 0xe00400
	s_mov_b64 s[38:39], 0xe00000
	v_mov_b32_e32 v252, 0xff800000
	s_branch .LBB0_343
